# G2 out/h stores write-through (sc0 sc1) so the grid barrier's L2 writeback is cheap
# speedup vs baseline: 1.1237x; 1.0144x over previous
.LBB0_133:
	ds_read_b128 v[178:181], v130
	ds_read_b128 v[182:185], v130 offset:32
	ds_read_b128 v[186:189], v130 offset:4608
	ds_read_b128 v[190:193], v130 offset:4640
	ds_read_b128 v[194:197], v131 offset:36864
	ds_read_b128 v[198:201], v131 offset:36896
	ds_read_b128 v[202:205], v131 offset:41472
	ds_read_b128 v[206:209], v131 offset:41504
	s_waitcnt vmcnt(15)
	ds_write_b128 v139, v[94:97] offset:18432
	buffer_load_dwordx4 v[94:97], v140, s[40:43], s0 offen
	s_waitcnt lgkmcnt(4)
	v_mfma_f32_32x32x16_bf16 v[50:65], v[178:181], v[194:197], v[50:65]
	s_add_u32 s24, s44, s0
	s_addc_u32 s25, vcc_lo, s1
	s_and_b32 s25, s25, 0xffff
	s_waitcnt lgkmcnt(2)
	v_mfma_f32_32x32x16_bf16 v[34:49], v[178:181], v[202:205], v[34:49]
	s_waitcnt vmcnt(15)
	ds_write_b128 v139, v[90:93] offset:55296
	buffer_load_dwordx4 v[90:93], v140, s[24:27], 0 offen
	v_mfma_f32_32x32x16_bf16 v[18:33], v[186:189], v[194:197], v[18:33]
	v_mfma_f32_32x32x16_bf16 v[2:17], v[186:189], v[202:205], v[2:17]
	s_add_i32 s34, s0, 0x11000
	ds_read_b128 v[178:181], v130 offset:64
	ds_read_b128 v[186:189], v130 offset:4672
	ds_read_b128 v[194:197], v131 offset:36928
	ds_read_b128 v[202:205], v131 offset:41536
	s_waitcnt vmcnt(15)
	ds_write_b128 v139, v[86:89] offset:23040
	buffer_load_dwordx4 v[86:89], v140, s[40:43], s34 offen
	v_mfma_f32_32x32x16_bf16 v[50:65], v[182:185], v[198:201], v[50:65]
	s_waitcnt lgkmcnt(7)
	v_mfma_f32_32x32x16_bf16 v[34:49], v[182:185], v[206:209], v[34:49]
	s_waitcnt vmcnt(15)
	ds_write_b128 v139, v[82:85] offset:59904
	buffer_load_dwordx4 v[82:85], v140, s[24:27], s33 offen
	v_mfma_f32_32x32x16_bf16 v[18:33], v[190:193], v[198:201], v[18:33]
	v_mfma_f32_32x32x16_bf16 v[2:17], v[190:193], v[206:209], v[2:17]
	s_add_i32 s34, s0, 0x22000
	ds_read_b128 v[182:185], v130 offset:96
	ds_read_b128 v[190:193], v130 offset:4704
	ds_read_b128 v[198:201], v131 offset:36960
	ds_read_b128 v[206:209], v131 offset:41568
	s_waitcnt vmcnt(15)
	ds_write_b128 v139, v[78:81] offset:27648
	buffer_load_dwordx4 v[78:81], v140, s[40:43], s34 offen
	s_waitcnt lgkmcnt(8)
	v_mfma_f32_32x32x16_bf16 v[50:65], v[178:181], v[194:197], v[50:65]
	s_waitcnt lgkmcnt(7)
	v_mfma_f32_32x32x16_bf16 v[34:49], v[178:181], v[202:205], v[34:49]
	s_waitcnt vmcnt(15)
	ds_write_b128 v139, v[74:77] offset:64512
	buffer_load_dwordx4 v[74:77], v140, s[24:27], s29 offen
	v_mfma_f32_32x32x16_bf16 v[18:33], v[186:189], v[194:197], v[18:33]
	v_mfma_f32_32x32x16_bf16 v[2:17], v[186:189], v[202:205], v[2:17]
	s_add_i32 s34, s0, 0x33000
	s_waitcnt vmcnt(15)
	ds_write_b128 v139, v[70:73] offset:32256
	buffer_load_dwordx4 v[70:73], v140, s[40:43], s34 offen
	s_waitcnt lgkmcnt(4)
	v_mfma_f32_32x32x16_bf16 v[50:65], v[182:185], v[198:201], v[50:65]
	s_waitcnt lgkmcnt(3)
	v_mfma_f32_32x32x16_bf16 v[34:49], v[182:185], v[206:209], v[34:49]
	s_waitcnt vmcnt(15)
	ds_write_b128 v142, v[66:69] offset:13824
	buffer_load_dwordx4 v[66:69], v140, s[24:27], s3 offen
	v_mfma_f32_32x32x16_bf16 v[18:33], v[190:193], v[198:201], v[18:33]
	v_mfma_f32_32x32x16_bf16 v[2:17], v[190:193], v[206:209], v[2:17]
	s_min_u32 s24, vcc_hi, 11
	s_lshl_b32 s34, s24, 7
	s_add_i32 s24, s34, 0x200
	s_waitcnt lgkmcnt(0)
	s_barrier
	ds_read_b128 v[178:181], v130 offset:18432
	ds_read_b128 v[182:185], v130 offset:18464
	ds_read_b128 v[186:189], v130 offset:23040
	ds_read_b128 v[190:193], v130 offset:23072
	ds_read_b128 v[194:197], v131 offset:55296
	ds_read_b128 v[198:201], v131 offset:55328
	ds_read_b128 v[202:205], v131 offset:59904
	ds_read_b128 v[206:209], v131 offset:59936
	s_waitcnt vmcnt(15)
	ds_write_b128 v139, v[102:105]
	buffer_load_dwordx4 v[102:105], v140, s[40:43], s24 offen
	s_waitcnt lgkmcnt(4)
	v_mfma_f32_32x32x16_bf16 v[50:65], v[178:181], v[194:197], v[50:65]
	s_add_u32 s24, s44, s24
	s_addc_u32 s25, vcc_lo, 0
	s_and_b32 s25, s25, 0xffff
	s_waitcnt lgkmcnt(2)
	v_mfma_f32_32x32x16_bf16 v[34:49], v[178:181], v[202:205], v[34:49]
	s_waitcnt vmcnt(15)
	ds_write_b128 v139, v[98:101] offset:36864
	buffer_load_dwordx4 v[98:101], v140, s[24:27], 0 offen
	v_mfma_f32_32x32x16_bf16 v[18:33], v[186:189], v[194:197], v[18:33]
	v_mfma_f32_32x32x16_bf16 v[2:17], v[186:189], v[202:205], v[2:17]
	s_add_i32 s35, s34, 0x11200
	ds_read_b128 v[178:181], v130 offset:18496
	ds_read_b128 v[186:189], v130 offset:23104
	ds_read_b128 v[194:197], v131 offset:55360
	ds_read_b128 v[202:205], v131 offset:59968
	s_waitcnt vmcnt(15)
	ds_write_b128 v139, v[106:109] offset:4608
	buffer_load_dwordx4 v[106:109], v140, s[40:43], s35 offen
	v_mfma_f32_32x32x16_bf16 v[50:65], v[182:185], v[198:201], v[50:65]
	s_waitcnt lgkmcnt(7)
	v_mfma_f32_32x32x16_bf16 v[34:49], v[182:185], v[206:209], v[34:49]
	s_waitcnt vmcnt(15)
	ds_write_b128 v139, v[110:113] offset:41472
	buffer_load_dwordx4 v[110:113], v140, s[24:27], s33 offen
	v_mfma_f32_32x32x16_bf16 v[18:33], v[190:193], v[198:201], v[18:33]
	v_mfma_f32_32x32x16_bf16 v[2:17], v[190:193], v[206:209], v[2:17]
	s_add_i32 s35, s34, 0x22200
	ds_read_b128 v[182:185], v130 offset:18528
	ds_read_b128 v[190:193], v130 offset:23136
	ds_read_b128 v[198:201], v131 offset:55392
	ds_read_b128 v[206:209], v131 offset:60000
	s_waitcnt vmcnt(15)
	ds_write_b128 v139, v[114:117] offset:9216
	buffer_load_dwordx4 v[114:117], v140, s[40:43], s35 offen
	s_waitcnt lgkmcnt(8)
	v_mfma_f32_32x32x16_bf16 v[50:65], v[178:181], v[194:197], v[50:65]
	s_waitcnt lgkmcnt(7)
	v_mfma_f32_32x32x16_bf16 v[34:49], v[178:181], v[202:205], v[34:49]
	s_waitcnt vmcnt(15)
	ds_write_b128 v139, v[118:121] offset:46080
	buffer_load_dwordx4 v[118:121], v140, s[24:27], s29 offen
	v_mfma_f32_32x32x16_bf16 v[18:33], v[186:189], v[194:197], v[18:33]
	v_mfma_f32_32x32x16_bf16 v[2:17], v[186:189], v[202:205], v[2:17]
	s_add_i32 s34, s34, 0x33200
	s_waitcnt vmcnt(15)
	ds_write_b128 v139, v[122:125] offset:13824
	buffer_load_dwordx4 v[122:125], v140, s[40:43], s34 offen
	s_waitcnt lgkmcnt(4)
	v_mfma_f32_32x32x16_bf16 v[50:65], v[182:185], v[198:201], v[50:65]
	s_waitcnt lgkmcnt(3)
	v_mfma_f32_32x32x16_bf16 v[34:49], v[182:185], v[206:209], v[34:49]
	s_waitcnt vmcnt(15)
	ds_write_b128 v139, v[126:129] offset:50688
	buffer_load_dwordx4 v[126:129], v140, s[24:27], s3 offen
	v_mfma_f32_32x32x16_bf16 v[18:33], v[190:193], v[198:201], v[18:33]
	v_mfma_f32_32x32x16_bf16 v[2:17], v[190:193], v[206:209], v[2:17]
	s_add_i32 vcc_hi, vcc_hi, 2
	s_add_u32 s0, s0, 0x100
	s_addc_u32 s1, s1, 0
	s_cmp_lt_u32 vcc_hi, 14
	s_waitcnt lgkmcnt(0)
	s_barrier
	s_cbranch_scc1 .LBB0_133
	s_waitcnt vmcnt(6)
	ds_read_b128 v[98:101], v130
	ds_read_b128 v[102:105], v131 offset:36864
	s_waitcnt vmcnt(5)
	ds_read_b128 v[106:109], v130 offset:32
	s_waitcnt vmcnt(4)
	ds_read_b128 v[110:113], v131 offset:36896
	s_waitcnt vmcnt(3)
	ds_read_b128 v[114:117], v131 offset:41472
	s_waitcnt vmcnt(2)
	ds_read_b128 v[118:121], v130 offset:4608
	s_waitcnt vmcnt(1)
	ds_read_b128 v[122:125], v130 offset:4640
	s_waitcnt vmcnt(0)
	ds_read_b128 v[126:129], v131 offset:41504
	s_waitcnt lgkmcnt(3)
	v_mfma_f32_32x32x16_bf16 v[34:49], v[98:101], v[114:117], v[34:49]
	ds_write_b128 v139, v[94:97] offset:18432
	v_mfma_f32_32x32x16_bf16 v[50:65], v[98:101], v[102:105], v[50:65]
	s_waitcnt lgkmcnt(3)
	v_mfma_f32_32x32x16_bf16 v[18:33], v[118:121], v[102:105], v[18:33]
	ds_write_b128 v139, v[90:93] offset:55296
	v_mfma_f32_32x32x16_bf16 v[2:17], v[118:121], v[114:117], v[2:17]
	v_mfma_f32_32x32x16_bf16 v[50:65], v[106:109], v[110:113], v[50:65]
	ds_read_b128 v[90:93], v130 offset:64
	ds_read_b128 v[94:97], v130 offset:4672
	ds_read_b128 v[98:101], v131 offset:36928
	ds_read_b128 v[102:105], v131 offset:41536
	ds_write_b128 v139, v[86:89] offset:23040
	s_waitcnt lgkmcnt(7)
	v_mfma_f32_32x32x16_bf16 v[34:49], v[106:109], v[126:129], v[34:49]
	v_mfma_f32_32x32x16_bf16 v[18:33], v[122:125], v[110:113], v[18:33]
	ds_write_b128 v139, v[82:85] offset:59904
	v_mfma_f32_32x32x16_bf16 v[2:17], v[122:125], v[126:129], v[2:17]
	s_waitcnt lgkmcnt(3)
	v_mfma_f32_32x32x16_bf16 v[50:65], v[90:93], v[98:101], v[50:65]
	ds_read_b128 v[82:85], v130 offset:96
	ds_read_b128 v[86:89], v130 offset:4704
	ds_read_b128 v[106:109], v131 offset:36960
	ds_read_b128 v[110:113], v131 offset:41568
	ds_write_b128 v139, v[78:81] offset:27648
	s_waitcnt lgkmcnt(7)
	v_mfma_f32_32x32x16_bf16 v[34:49], v[90:93], v[102:105], v[34:49]
	v_mfma_f32_32x32x16_bf16 v[18:33], v[94:97], v[98:101], v[18:33]
	ds_write_b128 v139, v[74:77] offset:64512
	v_mfma_f32_32x32x16_bf16 v[2:17], v[94:97], v[102:105], v[2:17]
	s_waitcnt lgkmcnt(3)
	v_mfma_f32_32x32x16_bf16 v[50:65], v[82:85], v[106:109], v[50:65]
	ds_write_b128 v139, v[70:73] offset:32256
	s_waitcnt lgkmcnt(3)
	v_mfma_f32_32x32x16_bf16 v[34:49], v[82:85], v[110:113], v[34:49]
	v_mfma_f32_32x32x16_bf16 v[18:33], v[86:89], v[106:109], v[18:33]
	ds_write_b128 v142, v[66:69] offset:13824
	v_mfma_f32_32x32x16_bf16 v[2:17], v[86:89], v[110:113], v[2:17]
	s_waitcnt lgkmcnt(0)
	s_barrier
	ds_read_b128 v[66:69], v130 offset:18432
	ds_read_b128 v[70:73], v131 offset:55296
	ds_read_b128 v[74:77], v130 offset:18464
	ds_read_b128 v[78:81], v131 offset:55328
	ds_read_b128 v[82:85], v131 offset:59904
	ds_read_b128 v[86:89], v130 offset:23040
	ds_read_b128 v[90:93], v130 offset:23072
	ds_read_b128 v[94:97], v131 offset:59936
	s_waitcnt lgkmcnt(6)
	v_mfma_f32_32x32x16_bf16 v[50:65], v[66:69], v[70:73], v[50:65]
	s_waitcnt lgkmcnt(3)
	v_mfma_f32_32x32x16_bf16 v[34:49], v[66:69], v[82:85], v[34:49]
	s_waitcnt lgkmcnt(2)
	v_mfma_f32_32x32x16_bf16 v[18:33], v[86:89], v[70:73], v[18:33]
	v_mfma_f32_32x32x16_bf16 v[2:17], v[86:89], v[82:85], v[2:17]
	v_mfma_f32_32x32x16_bf16 v[50:65], v[74:77], v[78:81], v[50:65]
	ds_read_b128 v[66:69], v130 offset:18496
	ds_read_b128 v[70:73], v130 offset:23104
	ds_read_b128 v[82:85], v131 offset:55360
	ds_read_b128 v[86:89], v131 offset:59968
	s_waitcnt lgkmcnt(4)
	v_mfma_f32_32x32x16_bf16 v[34:49], v[74:77], v[94:97], v[34:49]
	v_mfma_f32_32x32x16_bf16 v[18:33], v[90:93], v[78:81], v[18:33]
	v_mfma_f32_32x32x16_bf16 v[2:17], v[90:93], v[94:97], v[2:17]
	s_waitcnt lgkmcnt(1)
	v_mfma_f32_32x32x16_bf16 v[50:65], v[66:69], v[82:85], v[50:65]
	ds_read_b128 v[74:77], v130 offset:18528
	ds_read_b128 v[78:81], v130 offset:23136
	ds_read_b128 v[90:93], v131 offset:55392
	ds_read_b128 v[94:97], v131 offset:60000
	s_waitcnt lgkmcnt(4)
	v_mfma_f32_32x32x16_bf16 v[34:49], v[66:69], v[86:89], v[34:49]
	v_mfma_f32_32x32x16_bf16 v[18:33], v[70:73], v[82:85], v[18:33]
	v_mfma_f32_32x32x16_bf16 v[2:17], v[70:73], v[86:89], v[2:17]
	s_waitcnt lgkmcnt(1)
	v_mfma_f32_32x32x16_bf16 v[50:65], v[74:77], v[90:93], v[50:65]
	s_waitcnt lgkmcnt(0)
	v_mfma_f32_32x32x16_bf16 v[34:49], v[74:77], v[94:97], v[34:49]
	v_mfma_f32_32x32x16_bf16 v[18:33], v[78:81], v[90:93], v[18:33]
	v_mfma_f32_32x32x16_bf16 v[2:17], v[78:81], v[94:97], v[2:17]
	v_lshrrev_b32_e32 v227, 5, v136
	s_lshl_b32 s0, s51, 9
	v_lshl_add_u32 v223, v227, 12, v222
	v_add_u32_e32 v223, s0, v223
	v_mov_b32_e32 v228, v223
	global_load_dwordx4 v[98:101], v228, s[68:69]
	v_add_u32_e32 v228, 0x8000, v228
	global_load_dwordx4 v[102:105], v228, s[68:69]
	v_add_u32_e32 v228, 0x8000, v228
	global_load_dwordx4 v[106:109], v228, s[68:69]
	v_add_u32_e32 v228, 0x8000, v228
	global_load_dwordx4 v[110:113], v228, s[68:69]
	v_add_u32_e32 v228, 0x8000, v228
	global_load_dwordx4 v[114:117], v228, s[68:69]
	v_add_u32_e32 v228, 0x8000, v228
	global_load_dwordx4 v[118:121], v228, s[68:69]
	v_add_u32_e32 v228, 0x8000, v228
	global_load_dwordx4 v[122:125], v228, s[68:69]
	v_add_u32_e32 v228, 0x8000, v228
	global_load_dwordx4 v[126:129], v228, s[68:69]
	v_add_u32_e32 v228, 0x8000, v228
	global_load_dwordx4 v[178:181], v228, s[68:69]
	v_add_u32_e32 v228, 0x8000, v228
	global_load_dwordx4 v[182:185], v228, s[68:69]
	v_add_u32_e32 v228, 0x8000, v228
	global_load_dwordx4 v[186:189], v228, s[68:69]
	v_add_u32_e32 v228, 0x8000, v228
	global_load_dwordx4 v[190:193], v228, s[68:69]
	v_add_u32_e32 v228, 0x8000, v228
	global_load_dwordx4 v[194:197], v228, s[68:69]
	v_add_u32_e32 v228, 0x8000, v228
	global_load_dwordx4 v[198:201], v228, s[68:69]
	v_add_u32_e32 v228, 0x8000, v228
	global_load_dwordx4 v[202:205], v228, s[68:69]
	v_add_u32_e32 v228, 0x8000, v228
	global_load_dwordx4 v[206:209], v228, s[68:69]
	v_lshl_or_b32 v66, v138, 2, v141
	s_movk_i32 s0, 0x210
	v_and_or_b32 v67, v136, 64, v137
	v_mul_lo_u32 v66, v66, s0
	v_lshl_add_u32 v66, v67, 2, v66
	s_barrier
	s_nop 3
	ds_write2_b32 v66, v50, v34 offset1:32
	ds_write2_b32 v66, v51, v35 offset0:132 offset1:164
	v_add_u32_e32 v34, 0x400, v66
	ds_write2_b32 v34, v52, v36 offset0:8 offset1:40
	ds_write2_b32 v34, v53, v37 offset0:140 offset1:172
	v_add_u32_e32 v34, 0x1000, v66
	ds_write2_b32 v34, v54, v38 offset0:32 offset1:64
	ds_write2_b32 v34, v55, v39 offset0:164 offset1:196
	v_add_u32_e32 v34, 0x1400, v66
	ds_write2_b32 v34, v56, v40 offset0:40 offset1:72
	ds_write2_b32 v34, v57, v41 offset0:172 offset1:204
	v_add_u32_e32 v34, 0x2000, v66
	ds_write2_b32 v34, v58, v42 offset0:64 offset1:96
	ds_write2_b32 v34, v59, v43 offset0:196 offset1:228
	v_add_u32_e32 v34, 0x2400, v66
	ds_write2_b32 v34, v60, v44 offset0:72 offset1:104
	ds_write2_b32 v34, v61, v45 offset0:204 offset1:236
	v_add_u32_e32 v34, 0x3000, v66
	ds_write2_b32 v34, v62, v46 offset0:96 offset1:128
	v_add_u32_e32 v34, 0x3200, v66
	ds_write2_b32 v34, v63, v47 offset0:100 offset1:132
	v_add_u32_e32 v34, 0x3400, v66
	ds_write2_b32 v34, v64, v48 offset0:104 offset1:136
	v_add_u32_e32 v34, 0x3600, v66
	ds_write2_b32 v34, v65, v49 offset0:108 offset1:140
	v_add_u32_e32 v34, 0x4000, v66
	ds_write2_b32 v34, v18, v2 offset0:128 offset1:160
	v_add_u32_e32 v2, 0x4400, v66
	ds_write2_b32 v2, v19, v3 offset0:4 offset1:36
	ds_write2_b32 v2, v20, v4 offset0:136 offset1:168
	v_add_u32_e32 v2, 0x4800, v66
	ds_write2_b32 v2, v21, v5 offset0:12 offset1:44
	v_add_u32_e32 v2, 0x5000, v66
	ds_write2_b32 v2, v22, v6 offset0:160 offset1:192
	v_add_u32_e32 v2, 0x5400, v66
	ds_write2_b32 v2, v23, v7 offset0:36 offset1:68
	ds_write2_b32 v2, v24, v8 offset0:168 offset1:200
	v_add_u32_e32 v2, 0x5800, v66
	ds_write2_b32 v2, v25, v9 offset0:44 offset1:76
	v_add_u32_e32 v2, 0x6000, v66
	ds_write2_b32 v2, v26, v10 offset0:192 offset1:224
	v_add_u32_e32 v2, 0x6400, v66
	ds_write2_b32 v2, v27, v11 offset0:68 offset1:100
	ds_write2_b32 v2, v28, v12 offset0:200 offset1:232
	v_add_u32_e32 v2, 0x6800, v66
	ds_write2_b32 v2, v29, v13 offset0:76 offset1:108
	v_add_u32_e32 v2, 0x7200, v66
	ds_write2_b32 v2, v30, v14 offset0:96 offset1:128
	v_add_u32_e32 v2, 0x7400, v66
	ds_write2_b32 v2, v31, v15 offset0:100 offset1:132
	v_add_u32_e32 v2, 0x7600, v66
	ds_write2_b32 v2, v32, v16 offset0:104 offset1:136
	v_add_u32_e32 v2, 0x7800, v66
	ds_write2_b32 v2, v33, v17 offset0:108 offset1:140
	s_waitcnt lgkmcnt(0)
	s_barrier
	v_lshrrev_b32_e32 v227, 5, v136
	v_mul_u32_u24_e32 v225, 0x210, v227
	v_add_u32_e32 v225, v225, v222
	ds_read_b128 v[2:5], v225
	ds_read_b128 v[6:9], v225 offset:4224
	ds_read_b128 v[10:13], v225 offset:8448
	ds_read_b128 v[14:17], v225 offset:12672
	ds_read_b128 v[18:21], v225 offset:16896
	ds_read_b128 v[22:25], v225 offset:21120
	ds_read_b128 v[26:29], v225 offset:25344
	ds_read_b128 v[30:33], v225 offset:29568
	ds_read_b128 v[34:37], v225 offset:33792
	ds_read_b128 v[38:41], v225 offset:38016
	ds_read_b128 v[42:45], v225 offset:42240
	ds_read_b128 v[46:49], v225 offset:46464
	ds_read_b128 v[50:53], v225 offset:50688
	ds_read_b128 v[54:57], v225 offset:54912
	ds_read_b128 v[58:61], v225 offset:59136
	ds_read_b128 v[62:65], v225 offset:63360
	v_mul_u32_u24_e32 v224, 0x880, v227
	s_lshl_b32 s0, s51, 8
	v_lshrrev_b32_e32 v228, 1, v222
	v_add3_u32 v224, v224, v228, s0
	v_lshlrev_b32_e32 v226, 2, v227
	s_waitcnt lgkmcnt(0)
	s_waitcnt vmcnt(15)
	v_pk_fma_f32 v[2:3], v[2:3], v[210:211], v[98:99]
	v_pk_fma_f32 v[4:5], v[4:5], v[212:213], v[100:101]
	s_waitcnt vmcnt(14)
	v_pk_fma_f32 v[6:7], v[6:7], v[210:211], v[102:103]
	v_pk_fma_f32 v[8:9], v[8:9], v[212:213], v[104:105]
	s_waitcnt vmcnt(13)
	v_pk_fma_f32 v[10:11], v[10:11], v[210:211], v[106:107]
	v_pk_fma_f32 v[12:13], v[12:13], v[212:213], v[108:109]
	s_waitcnt vmcnt(12)
	v_pk_fma_f32 v[14:15], v[14:15], v[210:211], v[110:111]
	v_pk_fma_f32 v[16:17], v[16:17], v[212:213], v[112:113]
	s_waitcnt vmcnt(11)
	v_pk_fma_f32 v[18:19], v[18:19], v[210:211], v[114:115]
	v_pk_fma_f32 v[20:21], v[20:21], v[212:213], v[116:117]
	s_waitcnt vmcnt(10)
	v_pk_fma_f32 v[22:23], v[22:23], v[210:211], v[118:119]
	v_pk_fma_f32 v[24:25], v[24:25], v[212:213], v[120:121]
	s_waitcnt vmcnt(9)
	v_pk_fma_f32 v[26:27], v[26:27], v[210:211], v[122:123]
	v_pk_fma_f32 v[28:29], v[28:29], v[212:213], v[124:125]
	s_waitcnt vmcnt(8)
	v_pk_fma_f32 v[30:31], v[30:31], v[210:211], v[126:127]
	v_pk_fma_f32 v[32:33], v[32:33], v[212:213], v[128:129]
	s_waitcnt vmcnt(7)
	v_pk_fma_f32 v[34:35], v[34:35], v[210:211], v[178:179]
	v_pk_fma_f32 v[36:37], v[36:37], v[212:213], v[180:181]
	s_waitcnt vmcnt(6)
	v_pk_fma_f32 v[38:39], v[38:39], v[210:211], v[182:183]
	v_pk_fma_f32 v[40:41], v[40:41], v[212:213], v[184:185]
	s_waitcnt vmcnt(5)
	v_pk_fma_f32 v[42:43], v[42:43], v[210:211], v[186:187]
	v_pk_fma_f32 v[44:45], v[44:45], v[212:213], v[188:189]
	s_waitcnt vmcnt(4)
	v_pk_fma_f32 v[46:47], v[46:47], v[210:211], v[190:191]
	v_pk_fma_f32 v[48:49], v[48:49], v[212:213], v[192:193]
	s_waitcnt vmcnt(3)
	v_pk_fma_f32 v[50:51], v[50:51], v[210:211], v[194:195]
	v_pk_fma_f32 v[52:53], v[52:53], v[212:213], v[196:197]
	s_waitcnt vmcnt(2)
	v_pk_fma_f32 v[54:55], v[54:55], v[210:211], v[198:199]
	v_pk_fma_f32 v[56:57], v[56:57], v[212:213], v[200:201]
	s_waitcnt vmcnt(1)
	v_pk_fma_f32 v[58:59], v[58:59], v[210:211], v[202:203]
	v_pk_fma_f32 v[60:61], v[60:61], v[212:213], v[204:205]
	s_waitcnt vmcnt(0)
	v_pk_fma_f32 v[62:63], v[62:63], v[210:211], v[206:207]
	v_pk_fma_f32 v[64:65], v[64:65], v[212:213], v[208:209]
	v_mov_b32_e32 v228, v223
	global_store_dwordx4 v228, v[2:5], s[70:71] sc0 sc1
	v_add_u32_e32 v228, 0x8000, v228
	global_store_dwordx4 v228, v[6:9], s[70:71] sc0 sc1
	v_add_u32_e32 v228, 0x8000, v228
	global_store_dwordx4 v228, v[10:13], s[70:71] sc0 sc1
	v_add_u32_e32 v228, 0x8000, v228
	global_store_dwordx4 v228, v[14:17], s[70:71] sc0 sc1
	v_add_u32_e32 v228, 0x8000, v228
	global_store_dwordx4 v228, v[18:21], s[70:71] sc0 sc1
	v_add_u32_e32 v228, 0x8000, v228
	global_store_dwordx4 v228, v[22:25], s[70:71] sc0 sc1
	v_add_u32_e32 v228, 0x8000, v228
	global_store_dwordx4 v228, v[26:29], s[70:71] sc0 sc1
	v_add_u32_e32 v228, 0x8000, v228
	global_store_dwordx4 v228, v[30:33], s[70:71] sc0 sc1
	v_add_u32_e32 v228, 0x8000, v228
	global_store_dwordx4 v228, v[34:37], s[70:71] sc0 sc1
	v_add_u32_e32 v228, 0x8000, v228
	global_store_dwordx4 v228, v[38:41], s[70:71] sc0 sc1
	v_add_u32_e32 v228, 0x8000, v228
	global_store_dwordx4 v228, v[42:45], s[70:71] sc0 sc1
	v_add_u32_e32 v228, 0x8000, v228
	global_store_dwordx4 v228, v[46:49], s[70:71] sc0 sc1
	v_add_u32_e32 v228, 0x8000, v228
	global_store_dwordx4 v228, v[50:53], s[70:71] sc0 sc1
	v_add_u32_e32 v228, 0x8000, v228
	global_store_dwordx4 v228, v[54:57], s[70:71] sc0 sc1
	v_add_u32_e32 v228, 0x8000, v228
	global_store_dwordx4 v228, v[58:61], s[70:71] sc0 sc1
	v_add_u32_e32 v228, 0x8000, v228
	global_store_dwordx4 v228, v[62:65], s[70:71] sc0 sc1
	s_cmp_lg_u64 s[54:55], 0
	s_cbranch_scc0 .LBB0_122
	v_pk_add_f32 v[218:219], v[218:219], 1.0 op_sel_hi:[1,0]
	v_pk_add_f32 v[220:221], v[220:221], 1.0 op_sel_hi:[1,0]
	v_pk_mul_f32 v[214:215], v[214:215], v[218:219]
	v_pk_mul_f32 v[216:217], v[216:217], v[220:221]
	v_pk_mul_f32 v[98:99], v[2:3], v[2:3]
	v_pk_mul_f32 v[100:101], v[4:5], v[4:5]
	v_pk_mul_f32 v[102:103], v[6:7], v[6:7]
	v_pk_mul_f32 v[104:105], v[8:9], v[8:9]
	v_pk_mul_f32 v[106:107], v[10:11], v[10:11]
	v_pk_mul_f32 v[108:109], v[12:13], v[12:13]
	v_pk_mul_f32 v[110:111], v[14:15], v[14:15]
	v_pk_mul_f32 v[112:113], v[16:17], v[16:17]
	v_pk_mul_f32 v[114:115], v[18:19], v[18:19]
	v_pk_mul_f32 v[116:117], v[20:21], v[20:21]
	v_pk_mul_f32 v[118:119], v[22:23], v[22:23]
	v_pk_mul_f32 v[120:121], v[24:25], v[24:25]
	v_pk_mul_f32 v[122:123], v[26:27], v[26:27]
	v_pk_mul_f32 v[124:125], v[28:29], v[28:29]
	v_pk_mul_f32 v[126:127], v[30:31], v[30:31]
	v_pk_mul_f32 v[128:129], v[32:33], v[32:33]
	v_pk_mul_f32 v[178:179], v[34:35], v[34:35]
	v_pk_mul_f32 v[180:181], v[36:37], v[36:37]
	v_pk_mul_f32 v[182:183], v[38:39], v[38:39]
	v_pk_mul_f32 v[184:185], v[40:41], v[40:41]
	v_pk_mul_f32 v[186:187], v[42:43], v[42:43]
	v_pk_mul_f32 v[188:189], v[44:45], v[44:45]
	v_pk_mul_f32 v[190:191], v[46:47], v[46:47]
	v_pk_mul_f32 v[192:193], v[48:49], v[48:49]
	v_pk_mul_f32 v[194:195], v[50:51], v[50:51]
	v_pk_mul_f32 v[196:197], v[52:53], v[52:53]
	v_pk_mul_f32 v[198:199], v[54:55], v[54:55]
	v_pk_mul_f32 v[200:201], v[56:57], v[56:57]
	v_pk_mul_f32 v[202:203], v[58:59], v[58:59]
	v_pk_mul_f32 v[204:205], v[60:61], v[60:61]
	v_pk_mul_f32 v[206:207], v[62:63], v[62:63]
	v_pk_mul_f32 v[208:209], v[64:65], v[64:65]
	v_add_f32_e32 v229, v98, v99
	v_add_f32_e32 v230, v102, v103
	v_add_f32_e32 v231, v106, v107
	v_add_f32_e32 v232, v110, v111
	v_add_f32_e32 v233, v114, v115
	v_add_f32_e32 v234, v118, v119
	v_add_f32_e32 v235, v122, v123
	v_add_f32_e32 v236, v126, v127
	v_add_f32_e32 v237, v178, v179
	v_add_f32_e32 v238, v182, v183
	v_add_f32_e32 v239, v186, v187
	v_add_f32_e32 v240, v190, v191
	v_add_f32_e32 v241, v194, v195
	v_add_f32_e32 v242, v198, v199
	v_add_f32_e32 v243, v202, v203
	v_add_f32_e32 v244, v206, v207
	v_add_f32_e32 v229, v229, v100
	v_add_f32_e32 v230, v230, v104
	v_add_f32_e32 v231, v231, v108
	v_add_f32_e32 v232, v232, v112
	v_add_f32_e32 v233, v233, v116
	v_add_f32_e32 v234, v234, v120
	v_add_f32_e32 v235, v235, v124
	v_add_f32_e32 v236, v236, v128
	v_add_f32_e32 v237, v237, v180
	v_add_f32_e32 v238, v238, v184
	v_add_f32_e32 v239, v239, v188
	v_add_f32_e32 v240, v240, v192
	v_add_f32_e32 v241, v241, v196
	v_add_f32_e32 v242, v242, v200
	v_add_f32_e32 v243, v243, v204
	v_add_f32_e32 v244, v244, v208
	v_add_f32_e32 v229, v229, v101
	v_add_f32_e32 v230, v230, v105
	v_add_f32_e32 v231, v231, v109
	v_add_f32_e32 v232, v232, v113
	v_add_f32_e32 v233, v233, v117
	v_add_f32_e32 v234, v234, v121
	v_add_f32_e32 v235, v235, v125
	v_add_f32_e32 v236, v236, v129
	v_add_f32_e32 v237, v237, v181
	v_add_f32_e32 v238, v238, v185
	v_add_f32_e32 v239, v239, v189
	v_add_f32_e32 v240, v240, v193
	v_add_f32_e32 v241, v241, v197
	v_add_f32_e32 v242, v242, v201
	v_add_f32_e32 v243, v243, v205
	v_add_f32_e32 v244, v244, v209
	v_pk_mul_f32 v[2:3], v[2:3], v[214:215]
	v_pk_mul_f32 v[4:5], v[4:5], v[216:217]
	v_pk_mul_f32 v[6:7], v[6:7], v[214:215]
	v_pk_mul_f32 v[8:9], v[8:9], v[216:217]
	v_pk_mul_f32 v[10:11], v[10:11], v[214:215]
	v_pk_mul_f32 v[12:13], v[12:13], v[216:217]
	v_pk_mul_f32 v[14:15], v[14:15], v[214:215]
	v_pk_mul_f32 v[16:17], v[16:17], v[216:217]
	v_pk_mul_f32 v[18:19], v[18:19], v[214:215]
	v_pk_mul_f32 v[20:21], v[20:21], v[216:217]
	v_pk_mul_f32 v[22:23], v[22:23], v[214:215]
	v_pk_mul_f32 v[24:25], v[24:25], v[216:217]
	v_pk_mul_f32 v[26:27], v[26:27], v[214:215]
	v_pk_mul_f32 v[28:29], v[28:29], v[216:217]
	v_pk_mul_f32 v[30:31], v[30:31], v[214:215]
	v_pk_mul_f32 v[32:33], v[32:33], v[216:217]
	v_pk_mul_f32 v[34:35], v[34:35], v[214:215]
	v_pk_mul_f32 v[36:37], v[36:37], v[216:217]
	v_pk_mul_f32 v[38:39], v[38:39], v[214:215]
	v_pk_mul_f32 v[40:41], v[40:41], v[216:217]
	v_pk_mul_f32 v[42:43], v[42:43], v[214:215]
	v_pk_mul_f32 v[44:45], v[44:45], v[216:217]
	v_pk_mul_f32 v[46:47], v[46:47], v[214:215]
	v_pk_mul_f32 v[48:49], v[48:49], v[216:217]
	v_pk_mul_f32 v[50:51], v[50:51], v[214:215]
	v_pk_mul_f32 v[52:53], v[52:53], v[216:217]
	v_pk_mul_f32 v[54:55], v[54:55], v[214:215]
	v_pk_mul_f32 v[56:57], v[56:57], v[216:217]
	v_pk_mul_f32 v[58:59], v[58:59], v[214:215]
	v_pk_mul_f32 v[60:61], v[60:61], v[216:217]
	v_pk_mul_f32 v[62:63], v[62:63], v[214:215]
	v_pk_mul_f32 v[64:65], v[64:65], v[216:217]
	v_cvt_pk_bf16_f32 v98, v2, v3
	v_cvt_pk_bf16_f32 v99, v4, v5
	v_cvt_pk_bf16_f32 v102, v6, v7
	v_cvt_pk_bf16_f32 v103, v8, v9
	v_cvt_pk_bf16_f32 v106, v10, v11
	v_cvt_pk_bf16_f32 v107, v12, v13
	v_cvt_pk_bf16_f32 v110, v14, v15
	v_cvt_pk_bf16_f32 v111, v16, v17
	v_cvt_pk_bf16_f32 v114, v18, v19
	v_cvt_pk_bf16_f32 v115, v20, v21
	v_cvt_pk_bf16_f32 v118, v22, v23
	v_cvt_pk_bf16_f32 v119, v24, v25
	v_cvt_pk_bf16_f32 v122, v26, v27
	v_cvt_pk_bf16_f32 v123, v28, v29
	v_cvt_pk_bf16_f32 v126, v30, v31
	v_cvt_pk_bf16_f32 v127, v32, v33
	v_cvt_pk_bf16_f32 v178, v34, v35
	v_cvt_pk_bf16_f32 v179, v36, v37
	v_cvt_pk_bf16_f32 v182, v38, v39
	v_cvt_pk_bf16_f32 v183, v40, v41
	v_cvt_pk_bf16_f32 v186, v42, v43
	v_cvt_pk_bf16_f32 v187, v44, v45
	v_cvt_pk_bf16_f32 v190, v46, v47
	v_cvt_pk_bf16_f32 v191, v48, v49
	v_cvt_pk_bf16_f32 v194, v50, v51
	v_cvt_pk_bf16_f32 v195, v52, v53
	v_cvt_pk_bf16_f32 v198, v54, v55
	v_cvt_pk_bf16_f32 v199, v56, v57
	v_cvt_pk_bf16_f32 v202, v58, v59
	v_cvt_pk_bf16_f32 v203, v60, v61
	v_cvt_pk_bf16_f32 v206, v62, v63
	v_cvt_pk_bf16_f32 v207, v64, v65
	v_readlane_b32 s56, v248, 13
	v_readlane_b32 s57, v248, 14
	s_mul_i32 s0, s51, 0xa000
	s_lshl_b32 s1, s2, 2
	s_add_i32 s0, s0, s1
	s_add_u32 s56, s56, s0
	s_addc_u32 s57, s57, 0
	s_mul_i32 s0, s2, 0x880
	s_add_u32 s58, s8, s0
	s_addc_u32 s59, s9, 0
	v_mov_b32_e32 v228, v224
	global_store_dwordx2 v228, v[98:99], s[58:59] sc0 sc1
	v_add_u32_e32 v228, 0x4400, v228
	global_store_dwordx2 v228, v[102:103], s[58:59] sc0 sc1
	v_add_u32_e32 v228, 0x4400, v228
	global_store_dwordx2 v228, v[106:107], s[58:59] sc0 sc1
	v_add_u32_e32 v228, 0x4400, v228
	global_store_dwordx2 v228, v[110:111], s[58:59] sc0 sc1
	v_add_u32_e32 v228, 0x4400, v228
	global_store_dwordx2 v228, v[114:115], s[58:59] sc0 sc1
	v_add_u32_e32 v228, 0x4400, v228
	global_store_dwordx2 v228, v[118:119], s[58:59] sc0 sc1
	v_add_u32_e32 v228, 0x4400, v228
	global_store_dwordx2 v228, v[122:123], s[58:59] sc0 sc1
	v_add_u32_e32 v228, 0x4400, v228
	global_store_dwordx2 v228, v[126:127], s[58:59] sc0 sc1
	v_add_u32_e32 v228, 0x4400, v228
	global_store_dwordx2 v228, v[178:179], s[58:59] sc0 sc1
	v_add_u32_e32 v228, 0x4400, v228
	global_store_dwordx2 v228, v[182:183], s[58:59] sc0 sc1
	v_add_u32_e32 v228, 0x4400, v228
	global_store_dwordx2 v228, v[186:187], s[58:59] sc0 sc1
	v_add_u32_e32 v228, 0x4400, v228
	global_store_dwordx2 v228, v[190:191], s[58:59] sc0 sc1
	v_add_u32_e32 v228, 0x4400, v228
	global_store_dwordx2 v228, v[194:195], s[58:59] sc0 sc1
	v_add_u32_e32 v228, 0x4400, v228
	global_store_dwordx2 v228, v[198:199], s[58:59] sc0 sc1
	v_add_u32_e32 v228, 0x4400, v228
	global_store_dwordx2 v228, v[202:203], s[58:59] sc0 sc1
	v_add_u32_e32 v228, 0x4400, v228
	global_store_dwordx2 v228, v[206:207], s[58:59] sc0 sc1
	v_add_f32_dpp v229, v229, v229 quad_perm:[1,0,3,2] row_mask:0xf bank_mask:0xf
	v_add_f32_dpp v230, v230, v230 quad_perm:[1,0,3,2] row_mask:0xf bank_mask:0xf
	v_add_f32_dpp v231, v231, v231 quad_perm:[1,0,3,2] row_mask:0xf bank_mask:0xf
	v_add_f32_dpp v232, v232, v232 quad_perm:[1,0,3,2] row_mask:0xf bank_mask:0xf
	v_add_f32_dpp v233, v233, v233 quad_perm:[1,0,3,2] row_mask:0xf bank_mask:0xf
	v_add_f32_dpp v234, v234, v234 quad_perm:[1,0,3,2] row_mask:0xf bank_mask:0xf
	v_add_f32_dpp v235, v235, v235 quad_perm:[1,0,3,2] row_mask:0xf bank_mask:0xf
	v_add_f32_dpp v236, v236, v236 quad_perm:[1,0,3,2] row_mask:0xf bank_mask:0xf
	v_add_f32_dpp v237, v237, v237 quad_perm:[1,0,3,2] row_mask:0xf bank_mask:0xf
	v_add_f32_dpp v238, v238, v238 quad_perm:[1,0,3,2] row_mask:0xf bank_mask:0xf
	v_add_f32_dpp v239, v239, v239 quad_perm:[1,0,3,2] row_mask:0xf bank_mask:0xf
	v_add_f32_dpp v240, v240, v240 quad_perm:[1,0,3,2] row_mask:0xf bank_mask:0xf
	v_add_f32_dpp v241, v241, v241 quad_perm:[1,0,3,2] row_mask:0xf bank_mask:0xf
	v_add_f32_dpp v242, v242, v242 quad_perm:[1,0,3,2] row_mask:0xf bank_mask:0xf
	v_add_f32_dpp v243, v243, v243 quad_perm:[1,0,3,2] row_mask:0xf bank_mask:0xf
	v_add_f32_dpp v244, v244, v244 quad_perm:[1,0,3,2] row_mask:0xf bank_mask:0xf
	v_add_f32_dpp v229, v229, v229 quad_perm:[2,3,0,1] row_mask:0xf bank_mask:0xf
	v_add_f32_dpp v230, v230, v230 quad_perm:[2,3,0,1] row_mask:0xf bank_mask:0xf
	v_add_f32_dpp v231, v231, v231 quad_perm:[2,3,0,1] row_mask:0xf bank_mask:0xf
	v_add_f32_dpp v232, v232, v232 quad_perm:[2,3,0,1] row_mask:0xf bank_mask:0xf
	v_add_f32_dpp v233, v233, v233 quad_perm:[2,3,0,1] row_mask:0xf bank_mask:0xf
	v_add_f32_dpp v234, v234, v234 quad_perm:[2,3,0,1] row_mask:0xf bank_mask:0xf
	v_add_f32_dpp v235, v235, v235 quad_perm:[2,3,0,1] row_mask:0xf bank_mask:0xf
	v_add_f32_dpp v236, v236, v236 quad_perm:[2,3,0,1] row_mask:0xf bank_mask:0xf
	v_add_f32_dpp v237, v237, v237 quad_perm:[2,3,0,1] row_mask:0xf bank_mask:0xf
	v_add_f32_dpp v238, v238, v238 quad_perm:[2,3,0,1] row_mask:0xf bank_mask:0xf
	v_add_f32_dpp v239, v239, v239 quad_perm:[2,3,0,1] row_mask:0xf bank_mask:0xf
	v_add_f32_dpp v240, v240, v240 quad_perm:[2,3,0,1] row_mask:0xf bank_mask:0xf
	v_add_f32_dpp v241, v241, v241 quad_perm:[2,3,0,1] row_mask:0xf bank_mask:0xf
	v_add_f32_dpp v242, v242, v242 quad_perm:[2,3,0,1] row_mask:0xf bank_mask:0xf
	v_add_f32_dpp v243, v243, v243 quad_perm:[2,3,0,1] row_mask:0xf bank_mask:0xf
	v_add_f32_dpp v244, v244, v244 quad_perm:[2,3,0,1] row_mask:0xf bank_mask:0xf
	v_add_f32_dpp v229, v229, v229 row_ror:4 row_mask:0xf bank_mask:0xf
	v_add_f32_dpp v230, v230, v230 row_ror:4 row_mask:0xf bank_mask:0xf
	v_add_f32_dpp v231, v231, v231 row_ror:4 row_mask:0xf bank_mask:0xf
	v_add_f32_dpp v232, v232, v232 row_ror:4 row_mask:0xf bank_mask:0xf
	v_add_f32_dpp v233, v233, v233 row_ror:4 row_mask:0xf bank_mask:0xf
	v_add_f32_dpp v234, v234, v234 row_ror:4 row_mask:0xf bank_mask:0xf
	v_add_f32_dpp v235, v235, v235 row_ror:4 row_mask:0xf bank_mask:0xf
	v_add_f32_dpp v236, v236, v236 row_ror:4 row_mask:0xf bank_mask:0xf
	v_add_f32_dpp v237, v237, v237 row_ror:4 row_mask:0xf bank_mask:0xf
	v_add_f32_dpp v238, v238, v238 row_ror:4 row_mask:0xf bank_mask:0xf
	v_add_f32_dpp v239, v239, v239 row_ror:4 row_mask:0xf bank_mask:0xf
	v_add_f32_dpp v240, v240, v240 row_ror:4 row_mask:0xf bank_mask:0xf
	v_add_f32_dpp v241, v241, v241 row_ror:4 row_mask:0xf bank_mask:0xf
	v_add_f32_dpp v242, v242, v242 row_ror:4 row_mask:0xf bank_mask:0xf
	v_add_f32_dpp v243, v243, v243 row_ror:4 row_mask:0xf bank_mask:0xf
	v_add_f32_dpp v244, v244, v244 row_ror:4 row_mask:0xf bank_mask:0xf
	v_add_f32_dpp v229, v229, v229 row_ror:8 row_mask:0xf bank_mask:0xf
	v_add_f32_dpp v230, v230, v230 row_ror:8 row_mask:0xf bank_mask:0xf
	v_add_f32_dpp v231, v231, v231 row_ror:8 row_mask:0xf bank_mask:0xf
	v_add_f32_dpp v232, v232, v232 row_ror:8 row_mask:0xf bank_mask:0xf
	v_add_f32_dpp v233, v233, v233 row_ror:8 row_mask:0xf bank_mask:0xf
	v_add_f32_dpp v234, v234, v234 row_ror:8 row_mask:0xf bank_mask:0xf
	v_add_f32_dpp v235, v235, v235 row_ror:8 row_mask:0xf bank_mask:0xf
	v_add_f32_dpp v236, v236, v236 row_ror:8 row_mask:0xf bank_mask:0xf
	v_add_f32_dpp v237, v237, v237 row_ror:8 row_mask:0xf bank_mask:0xf
	v_add_f32_dpp v238, v238, v238 row_ror:8 row_mask:0xf bank_mask:0xf
	v_add_f32_dpp v239, v239, v239 row_ror:8 row_mask:0xf bank_mask:0xf
	v_add_f32_dpp v240, v240, v240 row_ror:8 row_mask:0xf bank_mask:0xf
	v_add_f32_dpp v241, v241, v241 row_ror:8 row_mask:0xf bank_mask:0xf
	v_add_f32_dpp v242, v242, v242 row_ror:8 row_mask:0xf bank_mask:0xf
	v_add_f32_dpp v243, v243, v243 row_ror:8 row_mask:0xf bank_mask:0xf
	v_add_f32_dpp v244, v244, v244 row_ror:8 row_mask:0xf bank_mask:0xf
	v_add_f32_dpp v229, v229, v229 row_bcast:15 row_mask:0xa bank_mask:0xf
	v_add_f32_dpp v230, v230, v230 row_bcast:15 row_mask:0xa bank_mask:0xf
	v_add_f32_dpp v231, v231, v231 row_bcast:15 row_mask:0xa bank_mask:0xf
	v_add_f32_dpp v232, v232, v232 row_bcast:15 row_mask:0xa bank_mask:0xf
	v_add_f32_dpp v233, v233, v233 row_bcast:15 row_mask:0xa bank_mask:0xf
	v_add_f32_dpp v234, v234, v234 row_bcast:15 row_mask:0xa bank_mask:0xf
	v_add_f32_dpp v235, v235, v235 row_bcast:15 row_mask:0xa bank_mask:0xf
	v_add_f32_dpp v236, v236, v236 row_bcast:15 row_mask:0xa bank_mask:0xf
	v_add_f32_dpp v237, v237, v237 row_bcast:15 row_mask:0xa bank_mask:0xf
	v_add_f32_dpp v238, v238, v238 row_bcast:15 row_mask:0xa bank_mask:0xf
	v_add_f32_dpp v239, v239, v239 row_bcast:15 row_mask:0xa bank_mask:0xf
	v_add_f32_dpp v240, v240, v240 row_bcast:15 row_mask:0xa bank_mask:0xf
	v_add_f32_dpp v241, v241, v241 row_bcast:15 row_mask:0xa bank_mask:0xf
	v_add_f32_dpp v242, v242, v242 row_bcast:15 row_mask:0xa bank_mask:0xf
	v_add_f32_dpp v243, v243, v243 row_bcast:15 row_mask:0xa bank_mask:0xf
	v_add_f32_dpp v244, v244, v244 row_bcast:15 row_mask:0xa bank_mask:0xf
	s_mov_b64 s[40:41], exec
	s_mov_b32 s0, 0x80000000
	s_mov_b32 s1, 0x80000000
	s_mov_b64 exec, s[0:1]
	global_store_dword v226, v229, s[56:57]
	global_store_dword v226, v230, s[56:57] offset:32
	global_store_dword v226, v231, s[56:57] offset:64
	global_store_dword v226, v232, s[56:57] offset:96
	global_store_dword v226, v233, s[56:57] offset:128
	global_store_dword v226, v234, s[56:57] offset:160
	global_store_dword v226, v235, s[56:57] offset:192
	global_store_dword v226, v236, s[56:57] offset:224
	global_store_dword v226, v237, s[56:57] offset:256
	global_store_dword v226, v238, s[56:57] offset:288
	global_store_dword v226, v239, s[56:57] offset:320
	global_store_dword v226, v240, s[56:57] offset:352
	global_store_dword v226, v241, s[56:57] offset:384
	global_store_dword v226, v242, s[56:57] offset:416
	global_store_dword v226, v243, s[56:57] offset:448
	global_store_dword v226, v244, s[56:57] offset:480
	s_mov_b64 exec, s[40:41]
	s_branch .LBB0_122
